# P5: modulated RMSNorm fused into the out-proj tile epilogue (x1 kept f32 in accumulators; bf16 x1 still stored for the P8 residual), on top of the fused P8 final norm
# baseline (speedup 1.0000x reference)
.LBB0_757:
	s_and_b64 vcc, exec, s[24:25]
	s_cbranch_vccnz .Lfz5_epi
	s_lshl_b32 s16, s14, 8
	v_add_u32_e32 v194, s16, v149
	v_lshl_or_b32 v166, s6, 8, v179
	v_readlane_b32 s60, v249, 9
	v_readlane_b32 s61, v249, 10
	s_ashr_i32 s0, s14, 3
	s_mul_hi_i32 s1, s0, 0x6000
	s_mulk_i32 s0, 0x6000
	s_add_u32 s0, s47, s0
	s_addc_u32 s1, s48, s1
	v_mov_b32_e32 v167, 0
	v_lshl_add_u32 v164, v194, 10, v166
	v_mov_b32_e32 v165, 0
	v_lshl_add_u64 v[170:171], v[166:167], 2, s[0:1]
	v_lshl_add_u64 v[172:173], v[164:165], 2, s[60:61]
	v_lshlrev_b32_e32 v144, 1, v164
	global_load_dwordx4 v[128:131], v[170:171], off
	global_load_dwordx4 v[132:135], v[170:171], off offset:16
	s_mov_b32 s62, 0x10000
	s_mov_b32 s63, 0
	s_mov_b32 s64, 0x50000
	s_mov_b32 s65, 0
	s_mov_b32 s66, 0x8000
	s_mov_b32 s67, 0x10000
	s_mov_b32 s68, 0x18000
	s_mov_b32 s69, 0x40000
	s_mov_b32 s70, 0x48000
	s_mov_b32 s71, 0x50000
	s_mov_b32 s72, 0x58000
	v_mov_b64_e32 v[174:175], v[172:173]
	global_load_dwordx4 v[200:203], v[174:175], off
	global_load_dwordx4 v[204:207], v[174:175], off offset:16
	v_lshl_add_u64 v[174:175], v[174:175], 0, s[62:63]
	global_load_dwordx4 v[208:211], v[174:175], off
	global_load_dwordx4 v[212:215], v[174:175], off offset:16
	global_load_dwordx4 v[186:189], v[170:171], off offset:512
	global_load_dwordx4 v[190:193], v[170:171], off offset:528
	v_lshl_add_u64 v[174:175], v[174:175], 0, s[62:63]
	global_load_dwordx4 v[216:219], v[174:175], off
	global_load_dwordx4 v[220:223], v[174:175], off offset:16
	v_lshl_add_u64 v[174:175], v[174:175], 0, s[62:63]
	global_load_dwordx4 v[224:227], v[174:175], off
	global_load_dwordx4 v[228:231], v[174:175], off offset:16
	v_lshl_add_u64 v[174:175], v[174:175], 0, s[64:65]
	global_load_dwordx4 v[232:235], v[174:175], off
	global_load_dwordx4 v[236:239], v[174:175], off offset:16
	v_lshl_add_u64 v[174:175], v[174:175], 0, s[62:63]
	global_load_dwordx4 v[240:243], v[174:175], off
	global_load_dwordx4 v[244:247], v[174:175], off offset:16
	s_waitcnt vmcnt(12)
	v_pk_fma_f32 v[124:125], v[124:125], v[128:129], v[200:201]
	v_pk_fma_f32 v[126:127], v[126:127], v[130:131], v[202:203]
	v_pk_fma_f32 v[120:121], v[120:121], v[132:133], v[204:205]
	v_pk_fma_f32 v[122:123], v[122:123], v[134:135], v[206:207]
	v_cvt_pk_bf16_f32 v204, v124, v125
	v_cvt_pk_bf16_f32 v205, v126, v127
	v_cvt_pk_bf16_f32 v206, v120, v121
	v_cvt_pk_bf16_f32 v207, v122, v123
	buffer_store_dwordx4 v[204:207], v144, s[8:11], 0 offen sc1
	v_lshl_add_u64 v[174:175], v[174:175], 0, s[62:63]
	global_load_dwordx4 v[200:203], v[174:175], off
	global_load_dwordx4 v[204:207], v[174:175], off offset:16
	s_waitcnt vmcnt(13)
	v_pk_fma_f32 v[116:117], v[116:117], v[128:129], v[208:209]
	v_pk_fma_f32 v[118:119], v[118:119], v[130:131], v[210:211]
	v_pk_fma_f32 v[112:113], v[112:113], v[132:133], v[212:213]
	v_pk_fma_f32 v[114:115], v[114:115], v[134:135], v[214:215]
	v_cvt_pk_bf16_f32 v212, v116, v117
	v_cvt_pk_bf16_f32 v213, v118, v119
	v_cvt_pk_bf16_f32 v214, v112, v113
	v_cvt_pk_bf16_f32 v215, v114, v115
	buffer_store_dwordx4 v[212:215], v144, s[8:11], s66 offen sc1
	v_lshl_add_u64 v[174:175], v[174:175], 0, s[62:63]
	global_load_dwordx4 v[208:211], v[174:175], off
	global_load_dwordx4 v[212:215], v[174:175], off offset:16
	s_waitcnt vmcnt(12)
	v_pk_fma_f32 v[108:109], v[108:109], v[128:129], v[216:217]
	v_pk_fma_f32 v[110:111], v[110:111], v[130:131], v[218:219]
	v_pk_fma_f32 v[104:105], v[104:105], v[132:133], v[220:221]
	v_pk_fma_f32 v[106:107], v[106:107], v[134:135], v[222:223]
	v_cvt_pk_bf16_f32 v220, v108, v109
	v_cvt_pk_bf16_f32 v221, v110, v111
	v_cvt_pk_bf16_f32 v222, v104, v105
	v_cvt_pk_bf16_f32 v223, v106, v107
	buffer_store_dwordx4 v[220:223], v144, s[8:11], s67 offen sc1
	v_mov_b64_e32 v[174:175], v[172:173]
	global_load_dwordx4 v[216:219], v[174:175], off offset:512
	global_load_dwordx4 v[220:223], v[174:175], off offset:528
	s_waitcnt vmcnt(13)
	v_pk_fma_f32 v[100:101], v[100:101], v[128:129], v[224:225]
	v_pk_fma_f32 v[102:103], v[102:103], v[130:131], v[226:227]
	v_pk_fma_f32 v[96:97], v[96:97], v[132:133], v[228:229]
	v_pk_fma_f32 v[98:99], v[98:99], v[134:135], v[230:231]
	v_cvt_pk_bf16_f32 v228, v100, v101
	v_cvt_pk_bf16_f32 v229, v102, v103
	v_cvt_pk_bf16_f32 v230, v96, v97
	v_cvt_pk_bf16_f32 v231, v98, v99
	buffer_store_dwordx4 v[228:231], v144, s[8:11], s68 offen sc1
	v_lshl_add_u64 v[174:175], v[174:175], 0, s[62:63]
	global_load_dwordx4 v[224:227], v[174:175], off offset:512
	global_load_dwordx4 v[228:231], v[174:175], off offset:528
	s_waitcnt vmcnt(14)
	v_pk_fma_f32 v[92:93], v[92:93], v[128:129], v[232:233]
	v_pk_fma_f32 v[94:95], v[94:95], v[130:131], v[234:235]
	v_pk_fma_f32 v[88:89], v[88:89], v[132:133], v[236:237]
	v_pk_fma_f32 v[90:91], v[90:91], v[134:135], v[238:239]
	v_cvt_pk_bf16_f32 v236, v92, v93
	v_cvt_pk_bf16_f32 v237, v94, v95
	v_cvt_pk_bf16_f32 v238, v88, v89
	v_cvt_pk_bf16_f32 v239, v90, v91
	buffer_store_dwordx4 v[236:239], v144, s[8:11], s69 offen sc1
	v_lshl_add_u64 v[174:175], v[174:175], 0, s[62:63]
	global_load_dwordx4 v[232:235], v[174:175], off offset:512
	global_load_dwordx4 v[236:239], v[174:175], off offset:528
	s_waitcnt vmcnt(15)
	v_pk_fma_f32 v[84:85], v[84:85], v[128:129], v[240:241]
	v_pk_fma_f32 v[86:87], v[86:87], v[130:131], v[242:243]
	v_pk_fma_f32 v[80:81], v[80:81], v[132:133], v[244:245]
	v_pk_fma_f32 v[82:83], v[82:83], v[134:135], v[246:247]
	v_cvt_pk_bf16_f32 v244, v84, v85
	v_cvt_pk_bf16_f32 v245, v86, v87
	v_cvt_pk_bf16_f32 v246, v80, v81
	v_cvt_pk_bf16_f32 v247, v82, v83
	buffer_store_dwordx4 v[244:247], v144, s[8:11], s70 offen sc1
	v_lshl_add_u64 v[174:175], v[174:175], 0, s[62:63]
	global_load_dwordx4 v[240:243], v[174:175], off offset:512
	global_load_dwordx4 v[244:247], v[174:175], off offset:528
	s_waitcnt vmcnt(15)
	v_pk_fma_f32 v[76:77], v[76:77], v[128:129], v[200:201]
	v_pk_fma_f32 v[78:79], v[78:79], v[130:131], v[202:203]
	v_pk_fma_f32 v[72:73], v[72:73], v[132:133], v[204:205]
	v_pk_fma_f32 v[74:75], v[74:75], v[134:135], v[206:207]
	v_cvt_pk_bf16_f32 v204, v76, v77
	v_cvt_pk_bf16_f32 v205, v78, v79
	v_cvt_pk_bf16_f32 v206, v72, v73
	v_cvt_pk_bf16_f32 v207, v74, v75
	buffer_store_dwordx4 v[204:207], v144, s[8:11], s71 offen sc1
	v_lshl_add_u64 v[174:175], v[174:175], 0, s[64:65]
	global_load_dwordx4 v[200:203], v[174:175], off offset:512
	global_load_dwordx4 v[204:207], v[174:175], off offset:528
	s_waitcnt vmcnt(15)
	v_pk_fma_f32 v[64:65], v[64:65], v[128:129], v[208:209]
	v_pk_fma_f32 v[66:67], v[66:67], v[130:131], v[210:211]
	v_pk_fma_f32 v[56:57], v[56:57], v[132:133], v[212:213]
	v_pk_fma_f32 v[58:59], v[58:59], v[134:135], v[214:215]
	v_cvt_pk_bf16_f32 v212, v64, v65
	v_cvt_pk_bf16_f32 v213, v66, v67
	v_cvt_pk_bf16_f32 v214, v56, v57
	v_cvt_pk_bf16_f32 v215, v58, v59
	buffer_store_dwordx4 v[212:215], v144, s[8:11], s72 offen sc1
	v_lshl_add_u64 v[174:175], v[174:175], 0, s[62:63]
	global_load_dwordx4 v[208:211], v[174:175], off offset:512
	global_load_dwordx4 v[212:215], v[174:175], off offset:528
	s_waitcnt vmcnt(15)
	v_pk_fma_f32 v[68:69], v[68:69], v[186:187], v[216:217]
	v_pk_fma_f32 v[70:71], v[70:71], v[188:189], v[218:219]
	v_pk_fma_f32 v[60:61], v[60:61], v[190:191], v[220:221]
	v_pk_fma_f32 v[62:63], v[62:63], v[192:193], v[222:223]
	v_cvt_pk_bf16_f32 v220, v68, v69
	v_cvt_pk_bf16_f32 v221, v70, v71
	v_cvt_pk_bf16_f32 v222, v60, v61
	v_cvt_pk_bf16_f32 v223, v62, v63
	buffer_store_dwordx4 v[220:223], v144, s[8:11], 0 offen offset:256 sc1
	v_lshl_add_u64 v[174:175], v[174:175], 0, s[62:63]
	global_load_dwordx4 v[216:219], v[174:175], off offset:512
	global_load_dwordx4 v[220:223], v[174:175], off offset:528
	s_waitcnt vmcnt(15)
	v_pk_fma_f32 v[52:53], v[52:53], v[186:187], v[224:225]
	v_pk_fma_f32 v[54:55], v[54:55], v[188:189], v[226:227]
	v_pk_fma_f32 v[48:49], v[48:49], v[190:191], v[228:229]
	v_pk_fma_f32 v[50:51], v[50:51], v[192:193], v[230:231]
	v_cvt_pk_bf16_f32 v228, v52, v53
	v_cvt_pk_bf16_f32 v229, v54, v55
	v_cvt_pk_bf16_f32 v230, v48, v49
	v_cvt_pk_bf16_f32 v231, v50, v51
	buffer_store_dwordx4 v[228:231], v144, s[8:11], s66 offen offset:256 sc1
	v_lshl_add_u64 v[174:175], v[174:175], 0, s[62:63]
	global_load_dwordx4 v[224:227], v[174:175], off offset:512
	global_load_dwordx4 v[228:231], v[174:175], off offset:528
	s_waitcnt vmcnt(15)
	v_pk_fma_f32 v[44:45], v[44:45], v[186:187], v[232:233]
	v_pk_fma_f32 v[46:47], v[46:47], v[188:189], v[234:235]
	v_pk_fma_f32 v[40:41], v[40:41], v[190:191], v[236:237]
	v_pk_fma_f32 v[42:43], v[42:43], v[192:193], v[238:239]
	v_cvt_pk_bf16_f32 v236, v44, v45
	v_cvt_pk_bf16_f32 v237, v46, v47
	v_cvt_pk_bf16_f32 v238, v40, v41
	v_cvt_pk_bf16_f32 v239, v42, v43
	buffer_store_dwordx4 v[236:239], v144, s[8:11], s67 offen offset:256 sc1
	s_waitcnt vmcnt(13)
	v_pk_fma_f32 v[36:37], v[36:37], v[186:187], v[240:241]
	v_pk_fma_f32 v[38:39], v[38:39], v[188:189], v[242:243]
	v_pk_fma_f32 v[32:33], v[32:33], v[190:191], v[244:245]
	v_pk_fma_f32 v[34:35], v[34:35], v[192:193], v[246:247]
	v_cvt_pk_bf16_f32 v244, v36, v37
	v_cvt_pk_bf16_f32 v245, v38, v39
	v_cvt_pk_bf16_f32 v246, v32, v33
	v_cvt_pk_bf16_f32 v247, v34, v35
	buffer_store_dwordx4 v[244:247], v144, s[8:11], s68 offen offset:256 sc1
	s_waitcnt vmcnt(11)
	v_pk_fma_f32 v[28:29], v[28:29], v[186:187], v[200:201]
	v_pk_fma_f32 v[30:31], v[30:31], v[188:189], v[202:203]
	v_pk_fma_f32 v[24:25], v[24:25], v[190:191], v[204:205]
	v_pk_fma_f32 v[26:27], v[26:27], v[192:193], v[206:207]
	v_cvt_pk_bf16_f32 v204, v28, v29
	v_cvt_pk_bf16_f32 v205, v30, v31
	v_cvt_pk_bf16_f32 v206, v24, v25
	v_cvt_pk_bf16_f32 v207, v26, v27
	buffer_store_dwordx4 v[204:207], v144, s[8:11], s69 offen offset:256 sc1
	s_waitcnt vmcnt(9)
	v_pk_fma_f32 v[20:21], v[20:21], v[186:187], v[208:209]
	v_pk_fma_f32 v[22:23], v[22:23], v[188:189], v[210:211]
	v_pk_fma_f32 v[16:17], v[16:17], v[190:191], v[212:213]
	v_pk_fma_f32 v[18:19], v[18:19], v[192:193], v[214:215]
	v_cvt_pk_bf16_f32 v212, v20, v21
	v_cvt_pk_bf16_f32 v213, v22, v23
	v_cvt_pk_bf16_f32 v214, v16, v17
	v_cvt_pk_bf16_f32 v215, v18, v19
	buffer_store_dwordx4 v[212:215], v144, s[8:11], s70 offen offset:256 sc1
	s_waitcnt vmcnt(7)
	v_pk_fma_f32 v[12:13], v[12:13], v[186:187], v[216:217]
	v_pk_fma_f32 v[14:15], v[14:15], v[188:189], v[218:219]
	v_pk_fma_f32 v[8:9], v[8:9], v[190:191], v[220:221]
	v_pk_fma_f32 v[10:11], v[10:11], v[192:193], v[222:223]
	v_cvt_pk_bf16_f32 v220, v12, v13
	v_cvt_pk_bf16_f32 v221, v14, v15
	v_cvt_pk_bf16_f32 v222, v8, v9
	v_cvt_pk_bf16_f32 v223, v10, v11
	buffer_store_dwordx4 v[220:223], v144, s[8:11], s71 offen offset:256 sc1
	s_waitcnt vmcnt(5)
	v_pk_fma_f32 v[4:5], v[4:5], v[186:187], v[224:225]
	v_pk_fma_f32 v[6:7], v[6:7], v[188:189], v[226:227]
	v_pk_fma_f32 v[0:1], v[0:1], v[190:191], v[228:229]
	v_pk_fma_f32 v[2:3], v[2:3], v[192:193], v[230:231]
	v_cvt_pk_bf16_f32 v228, v4, v5
	v_cvt_pk_bf16_f32 v229, v6, v7
	v_cvt_pk_bf16_f32 v230, v0, v1
	v_cvt_pk_bf16_f32 v231, v2, v3
	buffer_store_dwordx4 v[228:231], v144, s[8:11], s72 offen offset:256 sc1
	s_mov_b64 s[0:1], -1
	s_and_b64 vcc, exec, s[26:27]
	s_cbranch_vccz .LBB0_768
	s_waitcnt vmcnt(0)
	s_barrier
	s_and_saveexec_b64 s[0:1], s[92:93]
	s_cbranch_execz .LBB0_764
	s_mov_b64 s[42:43], exec
	v_mbcnt_lo_u32_b32 v0, s42, 0
	v_mbcnt_hi_u32_b32 v0, s43, v0
	v_cmp_eq_u32_e32 vcc, 0, v0
	s_and_saveexec_b64 s[4:5], vcc
	s_cbranch_execz .LBB0_761
	s_ashr_i32 s15, s14, 31
	s_lshl_b64 s[60:61], s[14:15], 2
	v_readlane_b32 s62, v249, 31
	v_readlane_b32 s63, v249, 32
	s_add_u32 s60, s62, s60
	s_addc_u32 s61, s63, s61
	s_bcnt1_i32_b64 s15, s[42:43]
	v_mov_b32_e32 v1, s15
	global_atomic_add v1, v145, v1, s[60:61] sc0

.LBB0_776:
	s_andn2_b64 vcc, exec, s[0:1]
	s_cbranch_vccz .LBB0_779
	s_mov_b32 s16, s14
	s_cmpk_lg_i32 s82, 0x100
	s_cselect_b32 s16, s16, -1
	s_mov_b32 s15, s6
	s_mov_b32 s6, s34
	s_mov_b32 s14, s36
	s_mov_b64 s[4:5], s[40:41]
	s_mov_b64 s[0:1], s[38:39]
	s_branch .LBB0_723
.Lfz5_epi:
	s_lshl_b32 s16, s14, 8
	v_add_u32_e32 v194, s16, v149
	v_lshl_or_b32 v166, s6, 8, v179
	v_readlane_b32 s60, v249, 9
	v_readlane_b32 s61, v249, 10
	s_ashr_i32 s0, s14, 3
	s_mul_hi_i32 s1, s0, 0x6000
	s_mulk_i32 s0, 0x6000
	s_add_u32 s74, s76, s0
	s_addc_u32 s75, s77, s1
	s_add_u32 s0, s47, s0
	s_addc_u32 s1, s48, s1
	v_mov_b32_e32 v167, 0
	v_lshl_add_u32 v164, v194, 10, v166
	v_mov_b32_e32 v165, 0
	v_lshl_add_u64 v[170:171], v[166:167], 2, s[0:1]
	v_lshl_add_u64 v[172:173], v[164:165], 2, s[60:61]
	v_lshlrev_b32_e32 v144, 1, v164
	global_load_dwordx4 v[128:131], v[170:171], off
	global_load_dwordx4 v[132:135], v[170:171], off offset:16
	s_mov_b32 s62, 0x10000
	s_mov_b32 s63, 0
	s_mov_b32 s64, 0x50000
	s_mov_b32 s65, 0
	v_mov_b64_e32 v[174:175], v[172:173]
	global_load_dwordx4 v[200:203], v[174:175], off
	global_load_dwordx4 v[204:207], v[174:175], off offset:16
	v_lshl_add_u64 v[174:175], v[174:175], 0, s[62:63]
	global_load_dwordx4 v[208:211], v[174:175], off
	global_load_dwordx4 v[212:215], v[174:175], off offset:16
	global_load_dwordx4 v[186:189], v[170:171], off offset:512
	global_load_dwordx4 v[190:193], v[170:171], off offset:528
	v_lshl_add_u64 v[174:175], v[174:175], 0, s[62:63]
	global_load_dwordx4 v[216:219], v[174:175], off
	global_load_dwordx4 v[220:223], v[174:175], off offset:16
	v_lshl_add_u64 v[174:175], v[174:175], 0, s[62:63]
	global_load_dwordx4 v[224:227], v[174:175], off
	global_load_dwordx4 v[228:231], v[174:175], off offset:16
	s_waitcnt vmcnt(8)
	v_pk_fma_f32 v[124:125], v[124:125], v[128:129], v[200:201]
	v_pk_fma_f32 v[126:127], v[126:127], v[130:131], v[202:203]
	v_pk_fma_f32 v[120:121], v[120:121], v[132:133], v[204:205]
	v_pk_fma_f32 v[122:123], v[122:123], v[134:135], v[206:207]
	v_cvt_pk_bf16_f32 v204, v124, v125
	v_cvt_pk_bf16_f32 v205, v126, v127
	v_cvt_pk_bf16_f32 v206, v120, v121
	v_cvt_pk_bf16_f32 v207, v122, v123
	buffer_store_dwordx4 v[204:207], v144, s[8:11], 0 offen sc1
	s_nop 0
	v_lshl_add_u64 v[174:175], v[174:175], 0, s[64:65]
	global_load_dwordx4 v[200:203], v[174:175], off
	global_load_dwordx4 v[204:207], v[174:175], off offset:16
	s_waitcnt vmcnt(9)
	v_pk_fma_f32 v[116:117], v[116:117], v[128:129], v[208:209]
	v_pk_fma_f32 v[118:119], v[118:119], v[130:131], v[210:211]
	v_pk_fma_f32 v[112:113], v[112:113], v[132:133], v[212:213]
	v_pk_fma_f32 v[114:115], v[114:115], v[134:135], v[214:215]
	v_cvt_pk_bf16_f32 v212, v116, v117
	v_cvt_pk_bf16_f32 v213, v118, v119
	v_cvt_pk_bf16_f32 v214, v112, v113
	v_cvt_pk_bf16_f32 v215, v114, v115
	v_add_u32_e32 v195, 0x8000, v144
	buffer_store_dwordx4 v[212:215], v195, s[8:11], 0 offen sc1
	s_nop 0
	v_lshl_add_u64 v[174:175], v[174:175], 0, s[62:63]
	global_load_dwordx4 v[208:211], v[174:175], off
	global_load_dwordx4 v[212:215], v[174:175], off offset:16
	s_waitcnt vmcnt(8)
	v_pk_fma_f32 v[108:109], v[108:109], v[128:129], v[216:217]
	v_pk_fma_f32 v[110:111], v[110:111], v[130:131], v[218:219]
	v_pk_fma_f32 v[104:105], v[104:105], v[132:133], v[220:221]
	v_pk_fma_f32 v[106:107], v[106:107], v[134:135], v[222:223]
	v_cvt_pk_bf16_f32 v220, v108, v109
	v_cvt_pk_bf16_f32 v221, v110, v111
	v_cvt_pk_bf16_f32 v222, v104, v105
	v_cvt_pk_bf16_f32 v223, v106, v107
	v_add_u32_e32 v195, 0x10000, v144
	buffer_store_dwordx4 v[220:223], v195, s[8:11], 0 offen sc1
	s_nop 0
	v_lshl_add_u64 v[174:175], v[174:175], 0, s[62:63]
	global_load_dwordx4 v[216:219], v[174:175], off
	global_load_dwordx4 v[220:223], v[174:175], off offset:16
	s_waitcnt vmcnt(9)
	v_pk_fma_f32 v[100:101], v[100:101], v[128:129], v[224:225]
	v_pk_fma_f32 v[102:103], v[102:103], v[130:131], v[226:227]
	v_pk_fma_f32 v[96:97], v[96:97], v[132:133], v[228:229]
	v_pk_fma_f32 v[98:99], v[98:99], v[134:135], v[230:231]
	v_cvt_pk_bf16_f32 v228, v100, v101
	v_cvt_pk_bf16_f32 v229, v102, v103
	v_cvt_pk_bf16_f32 v230, v96, v97
	v_cvt_pk_bf16_f32 v231, v98, v99
	v_add_u32_e32 v195, 0x18000, v144
	buffer_store_dwordx4 v[228:231], v195, s[8:11], 0 offen sc1
	s_nop 0
	v_lshl_add_u64 v[174:175], v[174:175], 0, s[62:63]
	global_load_dwordx4 v[224:227], v[174:175], off
	global_load_dwordx4 v[228:231], v[174:175], off offset:16
	s_waitcnt vmcnt(9)
	v_pk_fma_f32 v[92:93], v[92:93], v[128:129], v[200:201]
	v_pk_fma_f32 v[94:95], v[94:95], v[130:131], v[202:203]
	v_pk_fma_f32 v[88:89], v[88:89], v[132:133], v[204:205]
	v_pk_fma_f32 v[90:91], v[90:91], v[134:135], v[206:207]
	v_cvt_pk_bf16_f32 v204, v92, v93
	v_cvt_pk_bf16_f32 v205, v94, v95
	v_cvt_pk_bf16_f32 v206, v88, v89
	v_cvt_pk_bf16_f32 v207, v90, v91
	v_add_u32_e32 v195, 0x40000, v144
	buffer_store_dwordx4 v[204:207], v195, s[8:11], 0 offen sc1
	s_nop 0
	v_mov_b64_e32 v[174:175], v[172:173]
	global_load_dwordx4 v[200:203], v[174:175], off offset:512
	global_load_dwordx4 v[204:207], v[174:175], off offset:528
	s_waitcnt vmcnt(9)
	v_pk_fma_f32 v[84:85], v[84:85], v[128:129], v[208:209]
	v_pk_fma_f32 v[86:87], v[86:87], v[130:131], v[210:211]
	v_pk_fma_f32 v[80:81], v[80:81], v[132:133], v[212:213]
	v_pk_fma_f32 v[82:83], v[82:83], v[134:135], v[214:215]
	v_cvt_pk_bf16_f32 v212, v84, v85
	v_cvt_pk_bf16_f32 v213, v86, v87
	v_cvt_pk_bf16_f32 v214, v80, v81
	v_cvt_pk_bf16_f32 v215, v82, v83
	v_add_u32_e32 v195, 0x48000, v144
	buffer_store_dwordx4 v[212:215], v195, s[8:11], 0 offen sc1
	s_nop 0
	v_lshl_add_u64 v[174:175], v[174:175], 0, s[62:63]
	global_load_dwordx4 v[208:211], v[174:175], off offset:512
	global_load_dwordx4 v[212:215], v[174:175], off offset:528
	s_waitcnt vmcnt(9)
	v_pk_fma_f32 v[76:77], v[76:77], v[128:129], v[216:217]
	v_pk_fma_f32 v[78:79], v[78:79], v[130:131], v[218:219]
	v_pk_fma_f32 v[72:73], v[72:73], v[132:133], v[220:221]
	v_pk_fma_f32 v[74:75], v[74:75], v[134:135], v[222:223]
	v_cvt_pk_bf16_f32 v220, v76, v77
	v_cvt_pk_bf16_f32 v221, v78, v79
	v_cvt_pk_bf16_f32 v222, v72, v73
	v_cvt_pk_bf16_f32 v223, v74, v75
	v_add_u32_e32 v195, 0x50000, v144
	buffer_store_dwordx4 v[220:223], v195, s[8:11], 0 offen sc1
	s_nop 0
	v_lshl_add_u64 v[174:175], v[174:175], 0, s[62:63]
	global_load_dwordx4 v[216:219], v[174:175], off offset:512
	global_load_dwordx4 v[220:223], v[174:175], off offset:528
	s_waitcnt vmcnt(9)
	v_pk_fma_f32 v[64:65], v[64:65], v[128:129], v[224:225]
	v_pk_fma_f32 v[66:67], v[66:67], v[130:131], v[226:227]
	v_pk_fma_f32 v[56:57], v[56:57], v[132:133], v[228:229]
	v_pk_fma_f32 v[58:59], v[58:59], v[134:135], v[230:231]
	v_cvt_pk_bf16_f32 v228, v64, v65
	v_cvt_pk_bf16_f32 v229, v66, v67
	v_cvt_pk_bf16_f32 v230, v56, v57
	v_cvt_pk_bf16_f32 v231, v58, v59
	v_add_u32_e32 v195, 0x58000, v144
	buffer_store_dwordx4 v[228:231], v195, s[8:11], 0 offen sc1
	s_nop 0
	v_lshl_add_u64 v[174:175], v[174:175], 0, s[62:63]
	global_load_dwordx4 v[224:227], v[174:175], off offset:512
	global_load_dwordx4 v[228:231], v[174:175], off offset:528
	s_waitcnt vmcnt(9)
	v_pk_fma_f32 v[68:69], v[68:69], v[186:187], v[200:201]
	v_pk_fma_f32 v[70:71], v[70:71], v[188:189], v[202:203]
	v_pk_fma_f32 v[60:61], v[60:61], v[190:191], v[204:205]
	v_pk_fma_f32 v[62:63], v[62:63], v[192:193], v[206:207]
	v_cvt_pk_bf16_f32 v204, v68, v69
	v_cvt_pk_bf16_f32 v205, v70, v71
	v_cvt_pk_bf16_f32 v206, v60, v61
	v_cvt_pk_bf16_f32 v207, v62, v63
	buffer_store_dwordx4 v[204:207], v144, s[8:11], 0 offen offset:256 sc1
	s_nop 0
	v_lshl_add_u64 v[174:175], v[174:175], 0, s[64:65]
	global_load_dwordx4 v[200:203], v[174:175], off offset:512
	global_load_dwordx4 v[204:207], v[174:175], off offset:528
	s_waitcnt vmcnt(9)
	v_pk_fma_f32 v[52:53], v[52:53], v[186:187], v[208:209]
	v_pk_fma_f32 v[54:55], v[54:55], v[188:189], v[210:211]
	v_pk_fma_f32 v[48:49], v[48:49], v[190:191], v[212:213]
	v_pk_fma_f32 v[50:51], v[50:51], v[192:193], v[214:215]
	v_cvt_pk_bf16_f32 v212, v52, v53
	v_cvt_pk_bf16_f32 v213, v54, v55
	v_cvt_pk_bf16_f32 v214, v48, v49
	v_cvt_pk_bf16_f32 v215, v50, v51
	v_add_u32_e32 v195, 0x8000, v144
	buffer_store_dwordx4 v[212:215], v195, s[8:11], 0 offen offset:256 sc1
	s_nop 0
	v_lshl_add_u64 v[174:175], v[174:175], 0, s[62:63]
	global_load_dwordx4 v[208:211], v[174:175], off offset:512
	global_load_dwordx4 v[212:215], v[174:175], off offset:528
	s_waitcnt vmcnt(9)
	v_pk_fma_f32 v[44:45], v[44:45], v[186:187], v[216:217]
	v_pk_fma_f32 v[46:47], v[46:47], v[188:189], v[218:219]
	v_pk_fma_f32 v[40:41], v[40:41], v[190:191], v[220:221]
	v_pk_fma_f32 v[42:43], v[42:43], v[192:193], v[222:223]
	v_cvt_pk_bf16_f32 v220, v44, v45
	v_cvt_pk_bf16_f32 v221, v46, v47
	v_cvt_pk_bf16_f32 v222, v40, v41
	v_cvt_pk_bf16_f32 v223, v42, v43
	v_add_u32_e32 v195, 0x10000, v144
	buffer_store_dwordx4 v[220:223], v195, s[8:11], 0 offen offset:256 sc1
	s_nop 0
	v_lshl_add_u64 v[174:175], v[174:175], 0, s[62:63]
	global_load_dwordx4 v[216:219], v[174:175], off offset:512
	global_load_dwordx4 v[220:223], v[174:175], off offset:528
	s_waitcnt vmcnt(9)
	v_pk_fma_f32 v[36:37], v[36:37], v[186:187], v[224:225]
	v_pk_fma_f32 v[38:39], v[38:39], v[188:189], v[226:227]
	v_pk_fma_f32 v[32:33], v[32:33], v[190:191], v[228:229]
	v_pk_fma_f32 v[34:35], v[34:35], v[192:193], v[230:231]
	v_cvt_pk_bf16_f32 v228, v36, v37
	v_cvt_pk_bf16_f32 v229, v38, v39
	v_cvt_pk_bf16_f32 v230, v32, v33
	v_cvt_pk_bf16_f32 v231, v34, v35
	v_add_u32_e32 v195, 0x18000, v144
	buffer_store_dwordx4 v[228:231], v195, s[8:11], 0 offen offset:256 sc1
	s_nop 0
	v_lshl_add_u64 v[174:175], v[174:175], 0, s[62:63]
	global_load_dwordx4 v[224:227], v[174:175], off offset:512
	global_load_dwordx4 v[228:231], v[174:175], off offset:528
	s_waitcnt vmcnt(9)
	v_pk_fma_f32 v[28:29], v[28:29], v[186:187], v[200:201]
	v_pk_fma_f32 v[30:31], v[30:31], v[188:189], v[202:203]
	v_pk_fma_f32 v[24:25], v[24:25], v[190:191], v[204:205]
	v_pk_fma_f32 v[26:27], v[26:27], v[192:193], v[206:207]
	v_cvt_pk_bf16_f32 v204, v28, v29
	v_cvt_pk_bf16_f32 v205, v30, v31
	v_cvt_pk_bf16_f32 v206, v24, v25
	v_cvt_pk_bf16_f32 v207, v26, v27
	v_add_u32_e32 v195, 0x40000, v144
	buffer_store_dwordx4 v[204:207], v195, s[8:11], 0 offen offset:256 sc1
	s_waitcnt vmcnt(7)
	v_pk_fma_f32 v[20:21], v[20:21], v[186:187], v[208:209]
	v_pk_fma_f32 v[22:23], v[22:23], v[188:189], v[210:211]
	v_pk_fma_f32 v[16:17], v[16:17], v[190:191], v[212:213]
	v_pk_fma_f32 v[18:19], v[18:19], v[192:193], v[214:215]
	v_cvt_pk_bf16_f32 v212, v20, v21
	v_cvt_pk_bf16_f32 v213, v22, v23
	v_cvt_pk_bf16_f32 v214, v16, v17
	v_cvt_pk_bf16_f32 v215, v18, v19
	v_add_u32_e32 v195, 0x48000, v144
	buffer_store_dwordx4 v[212:215], v195, s[8:11], 0 offen offset:256 sc1
	s_waitcnt vmcnt(5)
	v_pk_fma_f32 v[12:13], v[12:13], v[186:187], v[216:217]
	v_pk_fma_f32 v[14:15], v[14:15], v[188:189], v[218:219]
	v_pk_fma_f32 v[8:9], v[8:9], v[190:191], v[220:221]
	v_pk_fma_f32 v[10:11], v[10:11], v[192:193], v[222:223]
	v_cvt_pk_bf16_f32 v220, v12, v13
	v_cvt_pk_bf16_f32 v221, v14, v15
	v_cvt_pk_bf16_f32 v222, v8, v9
	v_cvt_pk_bf16_f32 v223, v10, v11
	v_add_u32_e32 v195, 0x50000, v144
	buffer_store_dwordx4 v[220:223], v195, s[8:11], 0 offen offset:256 sc1
	s_waitcnt vmcnt(3)
	v_pk_fma_f32 v[4:5], v[4:5], v[186:187], v[224:225]
	v_pk_fma_f32 v[6:7], v[6:7], v[188:189], v[226:227]
	v_pk_fma_f32 v[0:1], v[0:1], v[190:191], v[228:229]
	v_pk_fma_f32 v[2:3], v[2:3], v[192:193], v[230:231]
	v_cvt_pk_bf16_f32 v228, v4, v5
	v_cvt_pk_bf16_f32 v229, v6, v7
	v_cvt_pk_bf16_f32 v230, v0, v1
	v_cvt_pk_bf16_f32 v231, v2, v3
	v_add_u32_e32 v195, 0x58000, v144
	buffer_store_dwordx4 v[228:231], v195, s[8:11], 0 offen offset:256 sc1
	s_add_u32 s0, s74, 0x3000
	s_addc_u32 s1, s75, 0
	v_lshl_add_u64 v[170:171], v[166:167], 2, s[0:1]
	global_load_dwordx4 v[128:131], v[170:171], off
	global_load_dwordx4 v[132:135], v[170:171], off offset:16
	global_load_dwordx4 v[186:189], v[170:171], off offset:512
	global_load_dwordx4 v[190:193], v[170:171], off offset:528
	v_pk_mul_f32 v[240:241], v[124:125], v[124:125]
	v_pk_mul_f32 v[244:245], v[116:117], v[116:117]
	v_pk_fma_f32 v[240:241], v[126:127], v[126:127], v[240:241]
	v_pk_fma_f32 v[244:245], v[118:119], v[118:119], v[244:245]
	v_pk_fma_f32 v[240:241], v[120:121], v[120:121], v[240:241]
	v_pk_fma_f32 v[244:245], v[112:113], v[112:113], v[244:245]
	v_pk_fma_f32 v[240:241], v[122:123], v[122:123], v[240:241]
	v_pk_fma_f32 v[244:245], v[114:115], v[114:115], v[244:245]
	v_pk_fma_f32 v[240:241], v[68:69], v[68:69], v[240:241]
	v_pk_fma_f32 v[244:245], v[52:53], v[52:53], v[244:245]
	v_pk_fma_f32 v[240:241], v[70:71], v[70:71], v[240:241]
	v_pk_fma_f32 v[244:245], v[54:55], v[54:55], v[244:245]
	v_pk_fma_f32 v[240:241], v[60:61], v[60:61], v[240:241]
	v_pk_fma_f32 v[244:245], v[48:49], v[48:49], v[244:245]
	v_pk_fma_f32 v[240:241], v[62:63], v[62:63], v[240:241]
	v_pk_fma_f32 v[244:245], v[50:51], v[50:51], v[244:245]
	v_add_f32_e32 v232, v240, v241
	v_add_f32_e32 v233, v244, v245
	v_pk_mul_f32 v[240:241], v[108:109], v[108:109]
	v_pk_mul_f32 v[244:245], v[100:101], v[100:101]
	v_pk_fma_f32 v[240:241], v[110:111], v[110:111], v[240:241]
	v_pk_fma_f32 v[244:245], v[102:103], v[102:103], v[244:245]
	v_pk_fma_f32 v[240:241], v[104:105], v[104:105], v[240:241]
	v_pk_fma_f32 v[244:245], v[96:97], v[96:97], v[244:245]
	v_pk_fma_f32 v[240:241], v[106:107], v[106:107], v[240:241]
	v_pk_fma_f32 v[244:245], v[98:99], v[98:99], v[244:245]
	v_pk_fma_f32 v[240:241], v[44:45], v[44:45], v[240:241]
	v_pk_fma_f32 v[244:245], v[36:37], v[36:37], v[244:245]
	v_pk_fma_f32 v[240:241], v[46:47], v[46:47], v[240:241]
	v_pk_fma_f32 v[244:245], v[38:39], v[38:39], v[244:245]
	v_pk_fma_f32 v[240:241], v[40:41], v[40:41], v[240:241]
	v_pk_fma_f32 v[244:245], v[32:33], v[32:33], v[244:245]
	v_pk_fma_f32 v[240:241], v[42:43], v[42:43], v[240:241]
	v_pk_fma_f32 v[244:245], v[34:35], v[34:35], v[244:245]
	v_add_f32_e32 v234, v240, v241
	v_add_f32_e32 v235, v244, v245
	v_pk_mul_f32 v[240:241], v[92:93], v[92:93]
	v_pk_mul_f32 v[244:245], v[84:85], v[84:85]
	v_pk_fma_f32 v[240:241], v[94:95], v[94:95], v[240:241]
	v_pk_fma_f32 v[244:245], v[86:87], v[86:87], v[244:245]
	v_pk_fma_f32 v[240:241], v[88:89], v[88:89], v[240:241]
	v_pk_fma_f32 v[244:245], v[80:81], v[80:81], v[244:245]
	v_pk_fma_f32 v[240:241], v[90:91], v[90:91], v[240:241]
	v_pk_fma_f32 v[244:245], v[82:83], v[82:83], v[244:245]
	v_pk_fma_f32 v[240:241], v[28:29], v[28:29], v[240:241]
	v_pk_fma_f32 v[244:245], v[20:21], v[20:21], v[244:245]
	v_pk_fma_f32 v[240:241], v[30:31], v[30:31], v[240:241]
	v_pk_fma_f32 v[244:245], v[22:23], v[22:23], v[244:245]
	v_pk_fma_f32 v[240:241], v[24:25], v[24:25], v[240:241]
	v_pk_fma_f32 v[244:245], v[16:17], v[16:17], v[244:245]
	v_pk_fma_f32 v[240:241], v[26:27], v[26:27], v[240:241]
	v_pk_fma_f32 v[244:245], v[18:19], v[18:19], v[244:245]
	v_add_f32_e32 v236, v240, v241
	v_add_f32_e32 v237, v244, v245
	v_pk_mul_f32 v[240:241], v[76:77], v[76:77]
	v_pk_mul_f32 v[244:245], v[64:65], v[64:65]
	v_pk_fma_f32 v[240:241], v[78:79], v[78:79], v[240:241]
	v_pk_fma_f32 v[244:245], v[66:67], v[66:67], v[244:245]
	v_pk_fma_f32 v[240:241], v[72:73], v[72:73], v[240:241]
	v_pk_fma_f32 v[244:245], v[56:57], v[56:57], v[244:245]
	v_pk_fma_f32 v[240:241], v[74:75], v[74:75], v[240:241]
	v_pk_fma_f32 v[244:245], v[58:59], v[58:59], v[244:245]
	v_pk_fma_f32 v[240:241], v[12:13], v[12:13], v[240:241]
	v_pk_fma_f32 v[244:245], v[4:5], v[4:5], v[244:245]
	v_pk_fma_f32 v[240:241], v[14:15], v[14:15], v[240:241]
	v_pk_fma_f32 v[244:245], v[6:7], v[6:7], v[244:245]
	v_pk_fma_f32 v[240:241], v[8:9], v[8:9], v[240:241]
	v_pk_fma_f32 v[244:245], v[0:1], v[0:1], v[244:245]
	v_pk_fma_f32 v[240:241], v[10:11], v[10:11], v[240:241]
	v_pk_fma_f32 v[244:245], v[2:3], v[2:3], v[244:245]
	v_add_f32_e32 v238, v240, v241
	v_add_f32_e32 v239, v244, v245
	v_xor_b32_e32 v242, 16, v199
	v_xor_b32_e32 v243, 32, v199
	v_lshlrev_b32_e32 v242, 2, v242
	v_lshlrev_b32_e32 v243, 2, v243
	ds_bpermute_b32 v224, v242, v232
	ds_bpermute_b32 v225, v242, v233
	ds_bpermute_b32 v226, v242, v234
	ds_bpermute_b32 v227, v242, v235
	ds_bpermute_b32 v228, v242, v236
	ds_bpermute_b32 v229, v242, v237
	ds_bpermute_b32 v230, v242, v238
	ds_bpermute_b32 v231, v242, v239
	s_waitcnt lgkmcnt(7)
	v_add_f32_e32 v232, v232, v224
	s_waitcnt lgkmcnt(6)
	v_add_f32_e32 v233, v233, v225
	s_waitcnt lgkmcnt(5)
	v_add_f32_e32 v234, v234, v226
	s_waitcnt lgkmcnt(4)
	v_add_f32_e32 v235, v235, v227
	s_waitcnt lgkmcnt(3)
	v_add_f32_e32 v236, v236, v228
	s_waitcnt lgkmcnt(2)
	v_add_f32_e32 v237, v237, v229
	s_waitcnt lgkmcnt(1)
	v_add_f32_e32 v238, v238, v230
	s_waitcnt lgkmcnt(0)
	v_add_f32_e32 v239, v239, v231
	ds_bpermute_b32 v224, v243, v232
	ds_bpermute_b32 v225, v243, v233
	ds_bpermute_b32 v226, v243, v234
	ds_bpermute_b32 v227, v243, v235
	ds_bpermute_b32 v228, v243, v236
	ds_bpermute_b32 v229, v243, v237
	ds_bpermute_b32 v230, v243, v238
	ds_bpermute_b32 v231, v243, v239
	s_waitcnt lgkmcnt(7)
	v_add_f32_e32 v232, v232, v224
	s_waitcnt lgkmcnt(6)
	v_add_f32_e32 v233, v233, v225
	s_waitcnt lgkmcnt(5)
	v_add_f32_e32 v234, v234, v226
	s_waitcnt lgkmcnt(4)
	v_add_f32_e32 v235, v235, v227
	s_waitcnt lgkmcnt(3)
	v_add_f32_e32 v236, v236, v228
	s_waitcnt lgkmcnt(2)
	v_add_f32_e32 v237, v237, v229
	s_waitcnt lgkmcnt(1)
	v_add_f32_e32 v238, v238, v230
	s_waitcnt lgkmcnt(0)
	v_add_f32_e32 v239, v239, v231
	s_add_u32 s70, s88, 0x1d00000
	s_addc_u32 s71, s89, 0
	v_lshlrev_b32_e32 v244, 6, v194
	v_bfe_u32 v245, v179, 5, 2
	s_lshl_b32 s66, s6, 2
	v_add_u32_e32 v245, s66, v245
	v_lshl_add_u32 v244, v245, 2, v244
	v_mov_b32_e32 v245, 0
	v_lshl_add_u64 v[246:247], v[244:245], 0, s[70:71]
	s_mov_b64 s[66:67], 0x2000
	v_lshl_add_u64 v[240:241], v[246:247], 0, s[66:67]
	v_cmp_gt_u32_e32 vcc, 16, v199
	s_and_saveexec_b64 s[42:43], vcc
	global_store_dword v[246:247], v232, off
	global_store_dword v[246:247], v233, off offset:1024
	global_store_dword v[246:247], v234, off offset:2048
	global_store_dword v[246:247], v235, off offset:3072
	global_store_dword v[240:241], v236, off
	global_store_dword v[240:241], v237, off offset:1024
	global_store_dword v[240:241], v238, off offset:2048
	global_store_dword v[240:241], v239, off offset:3072
	s_or_b64 exec, exec, s[42:43]
	s_waitcnt vmcnt(0)
	s_barrier
	s_and_saveexec_b64 s[0:1], s[92:93]
	s_cbranch_execz .Lfz5_sdone
	s_ashr_i32 s73, s14, 31
	s_mov_b32 s72, s14
	s_lshl_b64 s[72:73], s[72:73], 2
	v_readlane_b32 s62, v249, 31
	v_readlane_b32 s63, v249, 32
	s_add_u32 s72, s62, s72
	s_addc_u32 s73, s63, s73
	v_mov_b32_e32 v244, 1
	global_atomic_add v145, v244, s[72:73]
	s_mov_b32 s66, 0x40000
.Lfz5_poll:
	global_load_dword v244, v145, s[72:73] sc1
	s_waitcnt vmcnt(0)
	v_cmp_lt_u32_e32 vcc, 3, v244
	s_cbranch_vccnz .Lfz5_pok
	s_sleep 1
	s_add_i32 s66, s66, -1
	s_cmp_lg_u32 s66, 0
	s_cbranch_scc1 .Lfz5_poll

.Lfz5_sdone:
	s_or_b64 exec, exec, s[0:1]
	s_barrier
	v_lshlrev_b32_e32 v244, 6, v194
	v_lshrrev_b32_e32 v245, 4, v199
	v_lshl_add_u32 v244, v245, 4, v244
	v_mov_b32_e32 v245, 0
	v_lshl_add_u64 v[246:247], v[244:245], 0, s[70:71]
	s_mov_b64 s[66:67], 0x2000
	v_lshl_add_u64 v[240:241], v[246:247], 0, s[66:67]
	global_load_dwordx4 v[200:203], v[246:247], off
	global_load_dwordx4 v[204:207], v[246:247], off offset:1024
	global_load_dwordx4 v[208:211], v[246:247], off offset:2048
	global_load_dwordx4 v[212:215], v[246:247], off offset:3072
	global_load_dwordx4 v[216:219], v[240:241], off
	global_load_dwordx4 v[220:223], v[240:241], off offset:1024
	global_load_dwordx4 v[224:227], v[240:241], off offset:2048
	global_load_dwordx4 v[228:231], v[240:241], off offset:3072
	s_waitcnt vmcnt(7)
	v_add_f32_e32 v200, v200, v201
	v_add_f32_e32 v202, v202, v203
	v_add_f32_e32 v232, v200, v202
	s_waitcnt vmcnt(6)
	v_add_f32_e32 v204, v204, v205
	v_add_f32_e32 v206, v206, v207
	v_add_f32_e32 v233, v204, v206
	s_waitcnt vmcnt(5)
	v_add_f32_e32 v208, v208, v209
	v_add_f32_e32 v210, v210, v211
	v_add_f32_e32 v234, v208, v210
	s_waitcnt vmcnt(4)
	v_add_f32_e32 v212, v212, v213
	v_add_f32_e32 v214, v214, v215
	v_add_f32_e32 v235, v212, v214
	s_waitcnt vmcnt(3)
	v_add_f32_e32 v216, v216, v217
	v_add_f32_e32 v218, v218, v219
	v_add_f32_e32 v236, v216, v218
	s_waitcnt vmcnt(2)
	v_add_f32_e32 v220, v220, v221
	v_add_f32_e32 v222, v222, v223
	v_add_f32_e32 v237, v220, v222
	s_waitcnt vmcnt(1)
	v_add_f32_e32 v224, v224, v225
	v_add_f32_e32 v226, v226, v227
	v_add_f32_e32 v238, v224, v226
	s_waitcnt vmcnt(0)
	v_add_f32_e32 v228, v228, v229
	v_add_f32_e32 v230, v230, v231
	v_add_f32_e32 v239, v228, v230
	v_readfirstlane_b32 s66, v150
	v_readfirstlane_b32 s67, v151
	s_add_u32 s0, s74, 0x4000
	s_addc_u32 s1, s75, 0
	v_lshl_add_u64 v[170:171], v[166:167], 2, s[66:67]
	v_lshl_add_u64 v[172:173], v[166:167], 2, s[0:1]
	global_load_dwordx4 v[200:203], v[170:171], off
	global_load_dwordx4 v[204:207], v[170:171], off offset:16
	global_load_dwordx4 v[208:211], v[172:173], off
	global_load_dwordx4 v[212:215], v[172:173], off offset:16
	global_load_dwordx4 v[216:219], v[170:171], off offset:512
	global_load_dwordx4 v[220:223], v[170:171], off offset:528
	global_load_dwordx4 v[224:227], v[172:173], off offset:512
	global_load_dwordx4 v[228:231], v[172:173], off offset:528
	ds_bpermute_b32 v144, v242, v232
	ds_bpermute_b32 v195, v242, v233
	ds_bpermute_b32 v197, v242, v234
	ds_bpermute_b32 v198, v242, v235
	ds_bpermute_b32 v168, v242, v236
	ds_bpermute_b32 v169, v242, v237
	ds_bpermute_b32 v174, v242, v238
	ds_bpermute_b32 v175, v242, v239
	s_waitcnt lgkmcnt(7)
	v_add_f32_e32 v232, v232, v144
	s_waitcnt lgkmcnt(6)
	v_add_f32_e32 v233, v233, v195
	s_waitcnt lgkmcnt(5)
	v_add_f32_e32 v234, v234, v197
	s_waitcnt lgkmcnt(4)
	v_add_f32_e32 v235, v235, v198
	s_waitcnt lgkmcnt(3)
	v_add_f32_e32 v236, v236, v168
	s_waitcnt lgkmcnt(2)
	v_add_f32_e32 v237, v237, v169
	s_waitcnt lgkmcnt(1)
	v_add_f32_e32 v238, v238, v174
	s_waitcnt lgkmcnt(0)
	v_add_f32_e32 v239, v239, v175
	ds_bpermute_b32 v144, v243, v232
	ds_bpermute_b32 v195, v243, v233
	ds_bpermute_b32 v197, v243, v234
	ds_bpermute_b32 v198, v243, v235
	ds_bpermute_b32 v168, v243, v236
	ds_bpermute_b32 v169, v243, v237
	ds_bpermute_b32 v174, v243, v238
	ds_bpermute_b32 v175, v243, v239
	s_waitcnt lgkmcnt(7)
	v_add_f32_e32 v232, v232, v144
	s_waitcnt lgkmcnt(6)
	v_add_f32_e32 v233, v233, v195
	s_waitcnt lgkmcnt(5)
	v_add_f32_e32 v234, v234, v197
	s_waitcnt lgkmcnt(4)
	v_add_f32_e32 v235, v235, v198
	s_waitcnt lgkmcnt(3)
	v_add_f32_e32 v236, v236, v168
	s_waitcnt lgkmcnt(2)
	v_add_f32_e32 v237, v237, v169
	s_waitcnt lgkmcnt(1)
	v_add_f32_e32 v238, v238, v174
	s_waitcnt lgkmcnt(0)
	v_add_f32_e32 v239, v239, v175
	v_mul_f32_e32 v232, 0x3a800000, v232
	v_mul_f32_e32 v233, 0x3a800000, v233
	v_mul_f32_e32 v234, 0x3a800000, v234
	v_mul_f32_e32 v235, 0x3a800000, v235
	v_mul_f32_e32 v236, 0x3a800000, v236
	v_mul_f32_e32 v237, 0x3a800000, v237
	v_mul_f32_e32 v238, 0x3a800000, v238
	v_mul_f32_e32 v239, 0x3a800000, v239
	v_add_f32_e32 v232, 0x358637bd, v232
	v_add_f32_e32 v233, 0x358637bd, v233
	v_add_f32_e32 v234, 0x358637bd, v234
	v_add_f32_e32 v235, 0x358637bd, v235
	v_add_f32_e32 v236, 0x358637bd, v236
	v_add_f32_e32 v237, 0x358637bd, v237
	v_add_f32_e32 v238, 0x358637bd, v238
	v_add_f32_e32 v239, 0x358637bd, v239
	v_rsq_f32_e32 v240, v232
	v_rsq_f32_e32 v241, v233
	v_rsq_f32_e32 v242, v234
	v_rsq_f32_e32 v243, v235
	v_rsq_f32_e32 v244, v236
	v_rsq_f32_e32 v245, v237
	v_rsq_f32_e32 v246, v238
	v_rsq_f32_e32 v247, v239
	s_nop 0
	v_mul_f32_e32 v232, v232, v240
	v_mul_f32_e32 v233, v233, v241
	v_mul_f32_e32 v234, v234, v242
	v_mul_f32_e32 v235, v235, v243
	v_mul_f32_e32 v236, v236, v244
	v_mul_f32_e32 v237, v237, v245
	v_mul_f32_e32 v238, v238, v246
	v_mul_f32_e32 v239, v239, v247
	v_mul_f32_e32 v232, v232, v240
	v_mul_f32_e32 v233, v233, v241
	v_mul_f32_e32 v234, v234, v242
	v_mul_f32_e32 v235, v235, v243
	v_mul_f32_e32 v236, v236, v244
	v_mul_f32_e32 v237, v237, v245
	v_mul_f32_e32 v238, v238, v246
	v_mul_f32_e32 v239, v239, v247
	v_fma_f32 v232, v232, -0.5, 0.5
	v_fma_f32 v233, v233, -0.5, 0.5
	v_fma_f32 v234, v234, -0.5, 0.5
	v_fma_f32 v235, v235, -0.5, 0.5
	v_fma_f32 v236, v236, -0.5, 0.5
	v_fma_f32 v237, v237, -0.5, 0.5
	v_fma_f32 v238, v238, -0.5, 0.5
	v_fma_f32 v239, v239, -0.5, 0.5
	v_fma_f32 v240, v240, v232, v240
	v_fma_f32 v241, v241, v233, v241
	v_fma_f32 v242, v242, v234, v242
	v_fma_f32 v243, v243, v235, v243
	v_fma_f32 v244, v244, v236, v244
	v_fma_f32 v245, v245, v237, v245
	v_fma_f32 v246, v246, v238, v246
	v_fma_f32 v247, v247, v239, v247
	v_mov_b32_e32 v232, v240
	v_mov_b32_e32 v234, v241
	v_mov_b32_e32 v236, v242
	v_mov_b32_e32 v238, v243
	v_mov_b32_e32 v240, v244
	v_mov_b32_e32 v242, v245
	v_mov_b32_e32 v244, v246
	v_mov_b32_e32 v246, v247
	s_waitcnt vmcnt(0)
	v_pk_add_f32 v[208:209], v[208:209], 1.0 op_sel_hi:[1,0]
	v_pk_add_f32 v[210:211], v[210:211], 1.0 op_sel_hi:[1,0]
	v_pk_add_f32 v[212:213], v[212:213], 1.0 op_sel_hi:[1,0]
	v_pk_add_f32 v[214:215], v[214:215], 1.0 op_sel_hi:[1,0]
	v_pk_add_f32 v[224:225], v[224:225], 1.0 op_sel_hi:[1,0]
	v_pk_add_f32 v[226:227], v[226:227], 1.0 op_sel_hi:[1,0]
	v_pk_add_f32 v[228:229], v[228:229], 1.0 op_sel_hi:[1,0]
	v_pk_add_f32 v[230:231], v[230:231], 1.0 op_sel_hi:[1,0]
	v_pk_mul_f32 v[200:201], v[200:201], v[208:209]
	v_pk_mul_f32 v[202:203], v[202:203], v[210:211]
	v_pk_mul_f32 v[204:205], v[204:205], v[212:213]
	v_pk_mul_f32 v[206:207], v[206:207], v[214:215]
	v_pk_mul_f32 v[216:217], v[216:217], v[224:225]
	v_pk_mul_f32 v[218:219], v[218:219], v[226:227]
	v_pk_mul_f32 v[220:221], v[220:221], v[228:229]
	v_pk_mul_f32 v[222:223], v[222:223], v[230:231]
	v_readlane_b32 s66, v249, 34
	v_readlane_b32 s67, v249, 35
	s_mov_b64 s[62:63], 0x8000
	s_mov_b64 s[64:65], 0x28000
	s_nop 0
	v_lshl_add_u64 v[174:175], v[164:165], 1, s[66:67]
	v_pk_mul_f32 v[124:125], v[124:125], v[232:233] op_sel_hi:[1,0]
	v_pk_mul_f32 v[126:127], v[126:127], v[232:233] op_sel_hi:[1,0]
	v_pk_mul_f32 v[120:121], v[120:121], v[232:233] op_sel_hi:[1,0]
	v_pk_mul_f32 v[122:123], v[122:123], v[232:233] op_sel_hi:[1,0]
	v_pk_fma_f32 v[124:125], v[124:125], v[200:201], v[128:129]
	v_pk_fma_f32 v[126:127], v[126:127], v[202:203], v[130:131]
	v_pk_fma_f32 v[120:121], v[120:121], v[204:205], v[132:133]
	v_pk_fma_f32 v[122:123], v[122:123], v[206:207], v[134:135]
	v_cvt_pk_bf16_f32 v124, v124, v125
	v_cvt_pk_bf16_f32 v125, v126, v127
	v_cvt_pk_bf16_f32 v126, v120, v121
	v_cvt_pk_bf16_f32 v127, v122, v123
	global_store_dwordx4 v[174:175], v[124:127], off
	v_pk_mul_f32 v[68:69], v[68:69], v[232:233] op_sel_hi:[1,0]
	v_pk_mul_f32 v[70:71], v[70:71], v[232:233] op_sel_hi:[1,0]
	v_pk_mul_f32 v[60:61], v[60:61], v[232:233] op_sel_hi:[1,0]
	v_pk_mul_f32 v[62:63], v[62:63], v[232:233] op_sel_hi:[1,0]
	v_pk_fma_f32 v[68:69], v[68:69], v[216:217], v[186:187]
	v_pk_fma_f32 v[70:71], v[70:71], v[218:219], v[188:189]
	v_pk_fma_f32 v[60:61], v[60:61], v[220:221], v[190:191]
	v_pk_fma_f32 v[62:63], v[62:63], v[222:223], v[192:193]
	v_cvt_pk_bf16_f32 v68, v68, v69
	v_cvt_pk_bf16_f32 v69, v70, v71
	v_cvt_pk_bf16_f32 v70, v60, v61
	v_cvt_pk_bf16_f32 v71, v62, v63
	global_store_dwordx4 v[174:175], v[68:71], off offset:256
	v_lshl_add_u64 v[174:175], v[174:175], 0, s[62:63]
	v_pk_mul_f32 v[116:117], v[116:117], v[234:235] op_sel_hi:[1,0]
	v_pk_mul_f32 v[118:119], v[118:119], v[234:235] op_sel_hi:[1,0]
	v_pk_mul_f32 v[112:113], v[112:113], v[234:235] op_sel_hi:[1,0]
	v_pk_mul_f32 v[114:115], v[114:115], v[234:235] op_sel_hi:[1,0]
	v_pk_fma_f32 v[116:117], v[116:117], v[200:201], v[128:129]
	v_pk_fma_f32 v[118:119], v[118:119], v[202:203], v[130:131]
	v_pk_fma_f32 v[112:113], v[112:113], v[204:205], v[132:133]
	v_pk_fma_f32 v[114:115], v[114:115], v[206:207], v[134:135]
	v_cvt_pk_bf16_f32 v116, v116, v117
	v_cvt_pk_bf16_f32 v117, v118, v119
	v_cvt_pk_bf16_f32 v118, v112, v113
	v_cvt_pk_bf16_f32 v119, v114, v115
	global_store_dwordx4 v[174:175], v[116:119], off
	v_pk_mul_f32 v[52:53], v[52:53], v[234:235] op_sel_hi:[1,0]
	v_pk_mul_f32 v[54:55], v[54:55], v[234:235] op_sel_hi:[1,0]
	v_pk_mul_f32 v[48:49], v[48:49], v[234:235] op_sel_hi:[1,0]
	v_pk_mul_f32 v[50:51], v[50:51], v[234:235] op_sel_hi:[1,0]
	v_pk_fma_f32 v[52:53], v[52:53], v[216:217], v[186:187]
	v_pk_fma_f32 v[54:55], v[54:55], v[218:219], v[188:189]
	v_pk_fma_f32 v[48:49], v[48:49], v[220:221], v[190:191]
	v_pk_fma_f32 v[50:51], v[50:51], v[222:223], v[192:193]
	v_cvt_pk_bf16_f32 v52, v52, v53
	v_cvt_pk_bf16_f32 v53, v54, v55
	v_cvt_pk_bf16_f32 v54, v48, v49
	v_cvt_pk_bf16_f32 v55, v50, v51
	global_store_dwordx4 v[174:175], v[52:55], off offset:256
	v_lshl_add_u64 v[174:175], v[174:175], 0, s[62:63]
	v_pk_mul_f32 v[108:109], v[108:109], v[236:237] op_sel_hi:[1,0]
	v_pk_mul_f32 v[110:111], v[110:111], v[236:237] op_sel_hi:[1,0]
	v_pk_mul_f32 v[104:105], v[104:105], v[236:237] op_sel_hi:[1,0]
	v_pk_mul_f32 v[106:107], v[106:107], v[236:237] op_sel_hi:[1,0]
	v_pk_fma_f32 v[108:109], v[108:109], v[200:201], v[128:129]
	v_pk_fma_f32 v[110:111], v[110:111], v[202:203], v[130:131]
	v_pk_fma_f32 v[104:105], v[104:105], v[204:205], v[132:133]
	v_pk_fma_f32 v[106:107], v[106:107], v[206:207], v[134:135]
	v_cvt_pk_bf16_f32 v108, v108, v109
	v_cvt_pk_bf16_f32 v109, v110, v111
	v_cvt_pk_bf16_f32 v110, v104, v105
	v_cvt_pk_bf16_f32 v111, v106, v107
	global_store_dwordx4 v[174:175], v[108:111], off
	v_pk_mul_f32 v[44:45], v[44:45], v[236:237] op_sel_hi:[1,0]
	v_pk_mul_f32 v[46:47], v[46:47], v[236:237] op_sel_hi:[1,0]
	v_pk_mul_f32 v[40:41], v[40:41], v[236:237] op_sel_hi:[1,0]
	v_pk_mul_f32 v[42:43], v[42:43], v[236:237] op_sel_hi:[1,0]
	v_pk_fma_f32 v[44:45], v[44:45], v[216:217], v[186:187]
	v_pk_fma_f32 v[46:47], v[46:47], v[218:219], v[188:189]
	v_pk_fma_f32 v[40:41], v[40:41], v[220:221], v[190:191]
	v_pk_fma_f32 v[42:43], v[42:43], v[222:223], v[192:193]
	v_cvt_pk_bf16_f32 v44, v44, v45
	v_cvt_pk_bf16_f32 v45, v46, v47
	v_cvt_pk_bf16_f32 v46, v40, v41
	v_cvt_pk_bf16_f32 v47, v42, v43
	global_store_dwordx4 v[174:175], v[44:47], off offset:256
	v_lshl_add_u64 v[174:175], v[174:175], 0, s[62:63]
	v_pk_mul_f32 v[100:101], v[100:101], v[238:239] op_sel_hi:[1,0]
	v_pk_mul_f32 v[102:103], v[102:103], v[238:239] op_sel_hi:[1,0]
	v_pk_mul_f32 v[96:97], v[96:97], v[238:239] op_sel_hi:[1,0]
	v_pk_mul_f32 v[98:99], v[98:99], v[238:239] op_sel_hi:[1,0]
	v_pk_fma_f32 v[100:101], v[100:101], v[200:201], v[128:129]
	v_pk_fma_f32 v[102:103], v[102:103], v[202:203], v[130:131]
	v_pk_fma_f32 v[96:97], v[96:97], v[204:205], v[132:133]
	v_pk_fma_f32 v[98:99], v[98:99], v[206:207], v[134:135]
	v_cvt_pk_bf16_f32 v100, v100, v101
	v_cvt_pk_bf16_f32 v101, v102, v103
	v_cvt_pk_bf16_f32 v102, v96, v97
	v_cvt_pk_bf16_f32 v103, v98, v99
	global_store_dwordx4 v[174:175], v[100:103], off
	v_pk_mul_f32 v[36:37], v[36:37], v[238:239] op_sel_hi:[1,0]
	v_pk_mul_f32 v[38:39], v[38:39], v[238:239] op_sel_hi:[1,0]
	v_pk_mul_f32 v[32:33], v[32:33], v[238:239] op_sel_hi:[1,0]
	v_pk_mul_f32 v[34:35], v[34:35], v[238:239] op_sel_hi:[1,0]
	v_pk_fma_f32 v[36:37], v[36:37], v[216:217], v[186:187]
	v_pk_fma_f32 v[38:39], v[38:39], v[218:219], v[188:189]
	v_pk_fma_f32 v[32:33], v[32:33], v[220:221], v[190:191]
	v_pk_fma_f32 v[34:35], v[34:35], v[222:223], v[192:193]
	v_cvt_pk_bf16_f32 v36, v36, v37
	v_cvt_pk_bf16_f32 v37, v38, v39
	v_cvt_pk_bf16_f32 v38, v32, v33
	v_cvt_pk_bf16_f32 v39, v34, v35
	global_store_dwordx4 v[174:175], v[36:39], off offset:256
	v_lshl_add_u64 v[174:175], v[174:175], 0, s[64:65]
	v_pk_mul_f32 v[92:93], v[92:93], v[240:241] op_sel_hi:[1,0]
	v_pk_mul_f32 v[94:95], v[94:95], v[240:241] op_sel_hi:[1,0]
	v_pk_mul_f32 v[88:89], v[88:89], v[240:241] op_sel_hi:[1,0]
	v_pk_mul_f32 v[90:91], v[90:91], v[240:241] op_sel_hi:[1,0]
	v_pk_fma_f32 v[92:93], v[92:93], v[200:201], v[128:129]
	v_pk_fma_f32 v[94:95], v[94:95], v[202:203], v[130:131]
	v_pk_fma_f32 v[88:89], v[88:89], v[204:205], v[132:133]
	v_pk_fma_f32 v[90:91], v[90:91], v[206:207], v[134:135]
	v_cvt_pk_bf16_f32 v92, v92, v93
	v_cvt_pk_bf16_f32 v93, v94, v95
	v_cvt_pk_bf16_f32 v94, v88, v89
	v_cvt_pk_bf16_f32 v95, v90, v91
	global_store_dwordx4 v[174:175], v[92:95], off
	v_pk_mul_f32 v[28:29], v[28:29], v[240:241] op_sel_hi:[1,0]
	v_pk_mul_f32 v[30:31], v[30:31], v[240:241] op_sel_hi:[1,0]
	v_pk_mul_f32 v[24:25], v[24:25], v[240:241] op_sel_hi:[1,0]
	v_pk_mul_f32 v[26:27], v[26:27], v[240:241] op_sel_hi:[1,0]
	v_pk_fma_f32 v[28:29], v[28:29], v[216:217], v[186:187]
	v_pk_fma_f32 v[30:31], v[30:31], v[218:219], v[188:189]
	v_pk_fma_f32 v[24:25], v[24:25], v[220:221], v[190:191]
	v_pk_fma_f32 v[26:27], v[26:27], v[222:223], v[192:193]
	v_cvt_pk_bf16_f32 v28, v28, v29
	v_cvt_pk_bf16_f32 v29, v30, v31
	v_cvt_pk_bf16_f32 v30, v24, v25
	v_cvt_pk_bf16_f32 v31, v26, v27
	global_store_dwordx4 v[174:175], v[28:31], off offset:256
	v_lshl_add_u64 v[174:175], v[174:175], 0, s[62:63]
	v_pk_mul_f32 v[84:85], v[84:85], v[242:243] op_sel_hi:[1,0]
	v_pk_mul_f32 v[86:87], v[86:87], v[242:243] op_sel_hi:[1,0]
	v_pk_mul_f32 v[80:81], v[80:81], v[242:243] op_sel_hi:[1,0]
	v_pk_mul_f32 v[82:83], v[82:83], v[242:243] op_sel_hi:[1,0]
	v_pk_fma_f32 v[84:85], v[84:85], v[200:201], v[128:129]
	v_pk_fma_f32 v[86:87], v[86:87], v[202:203], v[130:131]
	v_pk_fma_f32 v[80:81], v[80:81], v[204:205], v[132:133]
	v_pk_fma_f32 v[82:83], v[82:83], v[206:207], v[134:135]
	v_cvt_pk_bf16_f32 v84, v84, v85
	v_cvt_pk_bf16_f32 v85, v86, v87
	v_cvt_pk_bf16_f32 v86, v80, v81
	v_cvt_pk_bf16_f32 v87, v82, v83
	global_store_dwordx4 v[174:175], v[84:87], off
	v_pk_mul_f32 v[20:21], v[20:21], v[242:243] op_sel_hi:[1,0]
	v_pk_mul_f32 v[22:23], v[22:23], v[242:243] op_sel_hi:[1,0]
	v_pk_mul_f32 v[16:17], v[16:17], v[242:243] op_sel_hi:[1,0]
	v_pk_mul_f32 v[18:19], v[18:19], v[242:243] op_sel_hi:[1,0]
	v_pk_fma_f32 v[20:21], v[20:21], v[216:217], v[186:187]
	v_pk_fma_f32 v[22:23], v[22:23], v[218:219], v[188:189]
	v_pk_fma_f32 v[16:17], v[16:17], v[220:221], v[190:191]
	v_pk_fma_f32 v[18:19], v[18:19], v[222:223], v[192:193]
	v_cvt_pk_bf16_f32 v20, v20, v21
	v_cvt_pk_bf16_f32 v21, v22, v23
	v_cvt_pk_bf16_f32 v22, v16, v17
	v_cvt_pk_bf16_f32 v23, v18, v19
	global_store_dwordx4 v[174:175], v[20:23], off offset:256
	v_lshl_add_u64 v[174:175], v[174:175], 0, s[62:63]
	v_pk_mul_f32 v[76:77], v[76:77], v[244:245] op_sel_hi:[1,0]
	v_pk_mul_f32 v[78:79], v[78:79], v[244:245] op_sel_hi:[1,0]
	v_pk_mul_f32 v[72:73], v[72:73], v[244:245] op_sel_hi:[1,0]
	v_pk_mul_f32 v[74:75], v[74:75], v[244:245] op_sel_hi:[1,0]
	v_pk_fma_f32 v[76:77], v[76:77], v[200:201], v[128:129]
	v_pk_fma_f32 v[78:79], v[78:79], v[202:203], v[130:131]
	v_pk_fma_f32 v[72:73], v[72:73], v[204:205], v[132:133]
	v_pk_fma_f32 v[74:75], v[74:75], v[206:207], v[134:135]
	v_cvt_pk_bf16_f32 v76, v76, v77
	v_cvt_pk_bf16_f32 v77, v78, v79
	v_cvt_pk_bf16_f32 v78, v72, v73
	v_cvt_pk_bf16_f32 v79, v74, v75
	global_store_dwordx4 v[174:175], v[76:79], off
	v_pk_mul_f32 v[12:13], v[12:13], v[244:245] op_sel_hi:[1,0]
	v_pk_mul_f32 v[14:15], v[14:15], v[244:245] op_sel_hi:[1,0]
	v_pk_mul_f32 v[8:9], v[8:9], v[244:245] op_sel_hi:[1,0]
	v_pk_mul_f32 v[10:11], v[10:11], v[244:245] op_sel_hi:[1,0]
	v_pk_fma_f32 v[12:13], v[12:13], v[216:217], v[186:187]
	v_pk_fma_f32 v[14:15], v[14:15], v[218:219], v[188:189]
	v_pk_fma_f32 v[8:9], v[8:9], v[220:221], v[190:191]
	v_pk_fma_f32 v[10:11], v[10:11], v[222:223], v[192:193]
	v_cvt_pk_bf16_f32 v12, v12, v13
	v_cvt_pk_bf16_f32 v13, v14, v15
	v_cvt_pk_bf16_f32 v14, v8, v9
	v_cvt_pk_bf16_f32 v15, v10, v11
	global_store_dwordx4 v[174:175], v[12:15], off offset:256
	v_lshl_add_u64 v[174:175], v[174:175], 0, s[62:63]
	v_pk_mul_f32 v[64:65], v[64:65], v[246:247] op_sel_hi:[1,0]
	v_pk_mul_f32 v[66:67], v[66:67], v[246:247] op_sel_hi:[1,0]
	v_pk_mul_f32 v[56:57], v[56:57], v[246:247] op_sel_hi:[1,0]
	v_pk_mul_f32 v[58:59], v[58:59], v[246:247] op_sel_hi:[1,0]
	v_pk_fma_f32 v[64:65], v[64:65], v[200:201], v[128:129]
	v_pk_fma_f32 v[66:67], v[66:67], v[202:203], v[130:131]
	v_pk_fma_f32 v[56:57], v[56:57], v[204:205], v[132:133]
	v_pk_fma_f32 v[58:59], v[58:59], v[206:207], v[134:135]
	v_cvt_pk_bf16_f32 v64, v64, v65
	v_cvt_pk_bf16_f32 v65, v66, v67
	v_cvt_pk_bf16_f32 v66, v56, v57
	v_cvt_pk_bf16_f32 v67, v58, v59
	global_store_dwordx4 v[174:175], v[64:67], off
	v_pk_mul_f32 v[4:5], v[4:5], v[246:247] op_sel_hi:[1,0]
	v_pk_mul_f32 v[6:7], v[6:7], v[246:247] op_sel_hi:[1,0]
	v_pk_mul_f32 v[0:1], v[0:1], v[246:247] op_sel_hi:[1,0]
	v_pk_mul_f32 v[2:3], v[2:3], v[246:247] op_sel_hi:[1,0]
	v_pk_fma_f32 v[4:5], v[4:5], v[216:217], v[186:187]
	v_pk_fma_f32 v[6:7], v[6:7], v[218:219], v[188:189]
	v_pk_fma_f32 v[0:1], v[0:1], v[220:221], v[190:191]
	v_pk_fma_f32 v[2:3], v[2:3], v[222:223], v[192:193]
	v_cvt_pk_bf16_f32 v4, v4, v5
	v_cvt_pk_bf16_f32 v5, v6, v7
	v_cvt_pk_bf16_f32 v6, v0, v1
	v_cvt_pk_bf16_f32 v7, v2, v3
	global_store_dwordx4 v[174:175], v[4:7], off offset:256
	s_branch .LBB0_772

.LBB0_780:
	s_mov_b32 s14, -1
	s_waitcnt vmcnt(0)
	s_waitcnt vmcnt(0) lgkmcnt(0)
	s_barrier
	s_and_saveexec_b64 s[0:1], s[92:93]
	s_cbranch_execz .LBB0_800
	s_cmp_lt_i32 s14, 0
	s_cbranch_scc1 .LBB0_785
	s_mov_b64 s[4:5], exec
	v_mbcnt_lo_u32_b32 v0, s4, 0
	v_mbcnt_hi_u32_b32 v0, s5, v0
	v_cmp_eq_u32_e32 vcc, 0, v0
	s_and_saveexec_b64 s[2:3], vcc
	s_cbranch_execz .LBB0_784
	s_mov_b32 s15, 0
	s_lshl_b64 s[8:9], s[14:15], 2
	v_readlane_b32 s10, v249, 31
	v_readlane_b32 s11, v249, 32
	s_add_u32 s8, s10, s8
	s_addc_u32 s9, s11, s9
	s_bcnt1_i32_b64 s4, s[4:5]
	v_mov_b32_e32 v0, 0
	v_mov_b32_e32 v1, s4
	global_atomic_add v0, v1, s[8:9]
